# P3 MIXED stores sc1 (write-through) so the full-barrier L2 write-back before P4 has less to flush
# baseline (speedup 1.0000x reference)
.LBB0_786:
	s_or_b64 exec, exec, s[26:27]
	global_store_dwordx4 v[130:131], v[120:123], off sc1
	global_store_dwordx4 v[128:129], v[124:127], off sc1
	v_mov_b32_e32 v133, v5
	v_or_b32_e32 v120, 16, v136
	v_ashrrev_i32_e32 v121, 31, v120
	v_lshlrev_b64 v[120:121], 10, v[120:121]
	v_lshl_add_u64 v[120:121], v[120:121], 0, v[6:7]
	v_lshlrev_b64 v[128:129], 1, v[120:121]
	v_lshl_add_u64 v[120:121], s[46:47], 0, v[128:129]
	v_lshl_add_u64 v[122:123], v[120:121], 0, v[148:149]
	v_lshl_add_u64 v[124:125], v[120:121], 0, v[150:151]
	v_mov_b32_e32 v134, v5
	v_mov_b32_e32 v135, v5
	v_mov_b32_e32 v138, v5
	s_waitcnt vmcnt(12)
	v_cndmask_b32_e64 v4, v208, v204, s[8:9]
	v_cndmask_b32_e64 v130, v209, v205, s[8:9]
	v_cndmask_b32_e64 v131, v210, v206, s[8:9]
	v_cndmask_b32_e64 v132, v211, v207, s[8:9]
	v_cndmask_b32_e64 v120, v204, v208, s[8:9]
	v_cndmask_b32_e64 v121, v205, v209, s[8:9]
	v_cndmask_b32_e64 v122, v206, v210, s[8:9]
	v_cndmask_b32_e64 v123, v207, v211, s[8:9]
	v_lshlrev_b64 v[204:205], 10, v[136:137]
	v_lshl_add_u64 v[206:207], v[204:205], 0, v[6:7]
	v_lshl_add_u64 v[206:207], v[206:207], 1, v[168:169]
	v_lshl_add_u64 v[244:245], s[46:47], 0, v[206:207]
	v_lshl_add_u64 v[246:247], v[244:245], 0, v[148:149]
	global_load_dwordx4 v[204:207], v[246:247], off nt
	v_lshlrev_b64 v[208:209], 10, v[136:137]
	v_lshl_add_u64 v[210:211], v[208:209], 0, v[6:7]
	v_lshl_add_u64 v[210:211], v[210:211], 1, v[168:169]
	v_lshl_add_u64 v[244:245], s[46:47], 0, v[210:211]
	v_lshl_add_u64 v[246:247], v[244:245], 0, v[150:151]
	global_load_dwordx4 v[208:211], v[246:247], off nt
	v_mov_b32_dpp v133, v120 row_ror:8 row_mask:0xf bank_mask:0xf
	v_mov_b32_dpp v134, v121 row_ror:8 row_mask:0xf bank_mask:0xf
	v_mov_b32_dpp v135, v122 row_ror:8 row_mask:0xf bank_mask:0xf
	v_mov_b32_dpp v138, v123 row_ror:8 row_mask:0xf bank_mask:0xf
	v_lshlrev_b32_e32 v120, 16, v4
	v_and_b32_e32 v121, 0xffff0000, v4
	v_lshlrev_b32_e32 v122, 16, v130
	v_and_b32_e32 v123, 0xffff0000, v130
	v_lshlrev_b32_e32 v124, 16, v131
	v_and_b32_e32 v125, 0xffff0000, v131
	v_lshlrev_b32_e32 v126, 16, v132
	v_and_b32_e32 v127, 0xffff0000, v132
	v_pk_mul_f32 v[118:119], v[118:119], v[122:123]
	v_pk_mul_f32 v[116:117], v[116:117], v[120:121]
	v_pk_mul_f32 v[114:115], v[114:115], v[126:127]
	v_pk_mul_f32 v[112:113], v[112:113], v[124:125]
	v_cvt_pk_bf16_f32 v4, v116, v117
	v_cvt_pk_bf16_f32 v116, v118, v119
	v_lshlrev_b32_e32 v120, 16, v135
	v_cvt_pk_bf16_f32 v117, v112, v113
	v_cvt_pk_bf16_f32 v118, v114, v115
	v_lshlrev_b32_e32 v112, 16, v133
	v_and_b32_e32 v113, 0xffff0000, v133
	v_lshlrev_b32_e32 v114, 16, v134
	v_and_b32_e32 v115, 0xffff0000, v134
	v_and_b32_e32 v121, 0xffff0000, v135
	v_lshlrev_b32_e32 v122, 16, v138
	v_and_b32_e32 v123, 0xffff0000, v138
	v_pk_mul_f32 v[110:111], v[110:111], v[114:115]
	v_pk_mul_f32 v[108:109], v[108:109], v[112:113]
	v_pk_mul_f32 v[106:107], v[106:107], v[122:123]
	v_pk_mul_f32 v[104:105], v[104:105], v[120:121]
	v_cvt_pk_bf16_f32 v108, v108, v109
	v_cvt_pk_bf16_f32 v109, v110, v111
	v_lshl_add_u64 v[112:113], s[40:41], 0, v[128:129]
	v_cvt_pk_bf16_f32 v110, v104, v105
	v_cvt_pk_bf16_f32 v111, v106, v107
	v_mov_b32_e32 v104, v5
	v_mov_b32_e32 v105, v5
	v_mov_b32_e32 v106, v5
	v_mov_b32_e32 v107, v5
	v_mov_b32_dpp v104, v108 row_ror:8 row_mask:0xf bank_mask:0xf
	v_mov_b32_dpp v105, v109 row_ror:8 row_mask:0xf bank_mask:0xf
	v_mov_b32_dpp v106, v110 row_ror:8 row_mask:0xf bank_mask:0xf
	v_mov_b32_dpp v107, v111 row_ror:8 row_mask:0xf bank_mask:0xf
	v_lshl_add_u64 v[114:115], v[112:113], 0, s[58:59]
	v_mov_b32_e32 v108, v4
	v_mov_b32_e32 v109, v116
	v_mov_b32_e32 v110, v117
	v_mov_b32_e32 v111, v118
	s_and_saveexec_b64 s[26:27], s[8:9]
	s_cbranch_execz .LBB0_788
	v_lshl_add_u64 v[120:121], v[112:113], 0, s[60:61]
	v_mov_b64_e32 v[114:115], v[112:113]
	v_mov_b32_e32 v108, v104
	v_mov_b32_e32 v109, v105
	v_mov_b32_e32 v110, v106
	v_mov_b32_e32 v111, v107
	v_mov_b32_e32 v104, v4
	v_mov_b32_e32 v105, v116
	v_mov_b32_e32 v106, v117
	v_mov_b32_e32 v107, v118
	v_mov_b64_e32 v[112:113], v[120:121]
.LBB0_788:
	s_or_b64 exec, exec, s[26:27]
	global_store_dwordx4 v[114:115], v[104:107], off sc1
	global_store_dwordx4 v[112:113], v[108:111], off sc1
	v_mov_b32_e32 v117, v5
	v_or_b32_e32 v104, 32, v136
	v_ashrrev_i32_e32 v105, 31, v104
	v_lshlrev_b64 v[104:105], 10, v[104:105]
	v_lshl_add_u64 v[104:105], v[104:105], 0, v[6:7]
	v_lshlrev_b64 v[112:113], 1, v[104:105]
	v_lshl_add_u64 v[104:105], s[46:47], 0, v[112:113]
	v_lshl_add_u64 v[106:107], v[104:105], 0, v[148:149]
	v_lshl_add_u64 v[108:109], v[104:105], 0, v[150:151]
	v_mov_b32_e32 v118, v5
	v_mov_b32_e32 v119, v5
	v_mov_b32_e32 v120, v5
	s_waitcnt vmcnt(14)
	v_cndmask_b32_e64 v4, v216, v212, s[8:9]
	v_cndmask_b32_e64 v114, v217, v213, s[8:9]
	v_cndmask_b32_e64 v115, v218, v214, s[8:9]
	v_cndmask_b32_e64 v116, v219, v215, s[8:9]
	v_cndmask_b32_e64 v104, v212, v216, s[8:9]
	v_cndmask_b32_e64 v105, v213, v217, s[8:9]
	v_cndmask_b32_e64 v106, v214, v218, s[8:9]
	v_cndmask_b32_e64 v107, v215, v219, s[8:9]
	v_mov_b32_dpp v117, v104 row_ror:8 row_mask:0xf bank_mask:0xf
	v_mov_b32_dpp v118, v105 row_ror:8 row_mask:0xf bank_mask:0xf
	v_mov_b32_dpp v119, v106 row_ror:8 row_mask:0xf bank_mask:0xf
	v_mov_b32_dpp v120, v107 row_ror:8 row_mask:0xf bank_mask:0xf
	v_lshlrev_b32_e32 v104, 16, v4
	v_and_b32_e32 v105, 0xffff0000, v4
	v_lshlrev_b32_e32 v106, 16, v114
	v_and_b32_e32 v107, 0xffff0000, v114
	v_lshlrev_b32_e32 v108, 16, v115
	v_and_b32_e32 v109, 0xffff0000, v115
	v_lshlrev_b32_e32 v110, 16, v116
	v_and_b32_e32 v111, 0xffff0000, v116
	v_pk_mul_f32 v[102:103], v[102:103], v[106:107]
	v_pk_mul_f32 v[100:101], v[100:101], v[104:105]
	v_pk_mul_f32 v[98:99], v[98:99], v[110:111]
	v_pk_mul_f32 v[96:97], v[96:97], v[108:109]
	v_cvt_pk_bf16_f32 v4, v100, v101
	v_cvt_pk_bf16_f32 v100, v102, v103
	v_lshlrev_b32_e32 v104, 16, v119
	v_cvt_pk_bf16_f32 v101, v96, v97
	v_cvt_pk_bf16_f32 v102, v98, v99
	v_lshlrev_b32_e32 v96, 16, v117
	v_and_b32_e32 v97, 0xffff0000, v117
	v_lshlrev_b32_e32 v98, 16, v118
	v_and_b32_e32 v99, 0xffff0000, v118
	v_and_b32_e32 v105, 0xffff0000, v119
	v_lshlrev_b32_e32 v106, 16, v120
	v_and_b32_e32 v107, 0xffff0000, v120
	v_pk_mul_f32 v[94:95], v[94:95], v[98:99]
	v_pk_mul_f32 v[92:93], v[92:93], v[96:97]
	v_pk_mul_f32 v[90:91], v[90:91], v[106:107]
	v_pk_mul_f32 v[88:89], v[88:89], v[104:105]
	v_cvt_pk_bf16_f32 v92, v92, v93
	v_cvt_pk_bf16_f32 v93, v94, v95
	v_lshl_add_u64 v[96:97], s[40:41], 0, v[112:113]
	v_cvt_pk_bf16_f32 v94, v88, v89
	v_cvt_pk_bf16_f32 v95, v90, v91
	v_mov_b32_e32 v88, v5
	v_mov_b32_e32 v89, v5
	v_mov_b32_e32 v90, v5
	v_mov_b32_e32 v91, v5
	v_mov_b32_dpp v88, v92 row_ror:8 row_mask:0xf bank_mask:0xf
	v_mov_b32_dpp v89, v93 row_ror:8 row_mask:0xf bank_mask:0xf
	v_mov_b32_dpp v90, v94 row_ror:8 row_mask:0xf bank_mask:0xf
	v_mov_b32_dpp v91, v95 row_ror:8 row_mask:0xf bank_mask:0xf
	v_lshl_add_u64 v[98:99], v[96:97], 0, s[58:59]
	v_mov_b32_e32 v92, v4
	v_mov_b32_e32 v93, v100
	v_mov_b32_e32 v94, v101
	v_mov_b32_e32 v95, v102
	s_and_saveexec_b64 s[26:27], s[8:9]
	s_cbranch_execz .LBB0_790
	v_lshl_add_u64 v[104:105], v[96:97], 0, s[60:61]
	v_mov_b64_e32 v[98:99], v[96:97]
	v_mov_b32_e32 v92, v88
	v_mov_b32_e32 v93, v89
	v_mov_b32_e32 v94, v90
	v_mov_b32_e32 v95, v91
	v_mov_b32_e32 v88, v4
	v_mov_b32_e32 v89, v100
	v_mov_b32_e32 v90, v101
	v_mov_b32_e32 v91, v102
	v_mov_b64_e32 v[96:97], v[104:105]
.LBB0_790:
	s_or_b64 exec, exec, s[26:27]
	global_store_dwordx4 v[98:99], v[88:91], off sc1
	global_store_dwordx4 v[96:97], v[92:95], off sc1
	v_mov_b32_e32 v101, v5
	v_or_b32_e32 v88, 48, v136
	v_ashrrev_i32_e32 v89, 31, v88
	v_lshlrev_b64 v[88:89], 10, v[88:89]
	v_lshl_add_u64 v[88:89], v[88:89], 0, v[6:7]
	v_lshlrev_b64 v[96:97], 1, v[88:89]
	v_lshl_add_u64 v[88:89], s[46:47], 0, v[96:97]
	v_lshl_add_u64 v[90:91], v[88:89], 0, v[148:149]
	v_lshl_add_u64 v[92:93], v[88:89], 0, v[150:151]
	v_mov_b32_e32 v102, v5
	v_mov_b32_e32 v103, v5
	v_mov_b32_e32 v104, v5
	s_waitcnt vmcnt(14)
	v_cndmask_b32_e64 v4, v224, v220, s[8:9]
	v_cndmask_b32_e64 v98, v225, v221, s[8:9]
	v_cndmask_b32_e64 v99, v226, v222, s[8:9]
	v_cndmask_b32_e64 v100, v227, v223, s[8:9]
	v_cndmask_b32_e64 v88, v220, v224, s[8:9]
	v_cndmask_b32_e64 v89, v221, v225, s[8:9]
	v_cndmask_b32_e64 v90, v222, v226, s[8:9]
	v_cndmask_b32_e64 v91, v223, v227, s[8:9]
	v_mov_b32_dpp v101, v88 row_ror:8 row_mask:0xf bank_mask:0xf
	v_mov_b32_dpp v102, v89 row_ror:8 row_mask:0xf bank_mask:0xf
	v_mov_b32_dpp v103, v90 row_ror:8 row_mask:0xf bank_mask:0xf
	v_mov_b32_dpp v104, v91 row_ror:8 row_mask:0xf bank_mask:0xf
	v_lshlrev_b32_e32 v88, 16, v4
	v_and_b32_e32 v89, 0xffff0000, v4
	v_lshlrev_b32_e32 v90, 16, v98
	v_and_b32_e32 v91, 0xffff0000, v98
	v_lshlrev_b32_e32 v92, 16, v99
	v_and_b32_e32 v93, 0xffff0000, v99
	v_lshlrev_b32_e32 v94, 16, v100
	v_and_b32_e32 v95, 0xffff0000, v100
	v_pk_mul_f32 v[86:87], v[86:87], v[90:91]
	v_pk_mul_f32 v[84:85], v[84:85], v[88:89]
	v_pk_mul_f32 v[82:83], v[82:83], v[94:95]
	v_pk_mul_f32 v[80:81], v[80:81], v[92:93]
	v_cvt_pk_bf16_f32 v4, v84, v85
	v_cvt_pk_bf16_f32 v84, v86, v87
	v_lshlrev_b32_e32 v88, 16, v103
	v_cvt_pk_bf16_f32 v85, v80, v81
	v_cvt_pk_bf16_f32 v86, v82, v83
	v_lshlrev_b32_e32 v80, 16, v101
	v_and_b32_e32 v81, 0xffff0000, v101
	v_lshlrev_b32_e32 v82, 16, v102
	v_and_b32_e32 v83, 0xffff0000, v102
	v_and_b32_e32 v89, 0xffff0000, v103
	v_lshlrev_b32_e32 v90, 16, v104
	v_and_b32_e32 v91, 0xffff0000, v104
	v_pk_mul_f32 v[78:79], v[78:79], v[82:83]
	v_pk_mul_f32 v[76:77], v[76:77], v[80:81]
	v_pk_mul_f32 v[74:75], v[74:75], v[90:91]
	v_pk_mul_f32 v[72:73], v[72:73], v[88:89]
	v_cvt_pk_bf16_f32 v76, v76, v77
	v_cvt_pk_bf16_f32 v77, v78, v79
	v_lshl_add_u64 v[80:81], s[40:41], 0, v[96:97]
	v_cvt_pk_bf16_f32 v78, v72, v73
	v_cvt_pk_bf16_f32 v79, v74, v75
	v_mov_b32_e32 v72, v5
	v_mov_b32_e32 v73, v5
	v_mov_b32_e32 v74, v5
	v_mov_b32_e32 v75, v5
	v_mov_b32_dpp v72, v76 row_ror:8 row_mask:0xf bank_mask:0xf
	v_mov_b32_dpp v73, v77 row_ror:8 row_mask:0xf bank_mask:0xf
	v_mov_b32_dpp v74, v78 row_ror:8 row_mask:0xf bank_mask:0xf
	v_mov_b32_dpp v75, v79 row_ror:8 row_mask:0xf bank_mask:0xf
	v_lshl_add_u64 v[82:83], v[80:81], 0, s[58:59]
	v_mov_b32_e32 v76, v4
	v_mov_b32_e32 v77, v84
	v_mov_b32_e32 v78, v85
	v_mov_b32_e32 v79, v86
	s_and_saveexec_b64 s[26:27], s[8:9]
	s_cbranch_execz .LBB0_792
	v_lshl_add_u64 v[88:89], v[80:81], 0, s[60:61]
	v_mov_b64_e32 v[82:83], v[80:81]
	v_mov_b32_e32 v76, v72
	v_mov_b32_e32 v77, v73
	v_mov_b32_e32 v78, v74
	v_mov_b32_e32 v79, v75
	v_mov_b32_e32 v72, v4
	v_mov_b32_e32 v73, v84
	v_mov_b32_e32 v74, v85
	v_mov_b32_e32 v75, v86
	v_mov_b64_e32 v[80:81], v[88:89]
.LBB0_792:
	s_or_b64 exec, exec, s[26:27]
	global_store_dwordx4 v[82:83], v[72:75], off sc1
	global_store_dwordx4 v[80:81], v[76:79], off sc1
	v_mov_b32_e32 v87, v5
	v_lshlrev_b64 v[72:73], 10, v[136:137]
	v_lshl_add_u64 v[72:73], v[72:73], 0, v[6:7]
	v_lshl_add_u64 v[82:83], v[72:73], 1, v[162:163]
	v_lshl_add_u64 v[74:75], s[46:47], 0, v[82:83]
	v_lshl_add_u64 v[76:77], v[74:75], 0, v[148:149]
	v_lshl_add_u64 v[78:79], v[74:75], 0, v[150:151]
	v_mov_b32_e32 v88, v5
	v_mov_b32_e32 v89, v5
	v_mov_b32_e32 v90, v5
	s_waitcnt vmcnt(14)
	v_cndmask_b32_e64 v4, v232, v228, s[8:9]
	v_cndmask_b32_e64 v84, v233, v229, s[8:9]
	v_cndmask_b32_e64 v85, v234, v230, s[8:9]
	v_cndmask_b32_e64 v86, v235, v231, s[8:9]
	v_cndmask_b32_e64 v74, v228, v232, s[8:9]
	v_cndmask_b32_e64 v75, v229, v233, s[8:9]
	v_cndmask_b32_e64 v76, v230, v234, s[8:9]
	v_cndmask_b32_e64 v77, v231, v235, s[8:9]
	v_mov_b32_dpp v87, v74 row_ror:8 row_mask:0xf bank_mask:0xf
	v_mov_b32_dpp v88, v75 row_ror:8 row_mask:0xf bank_mask:0xf
	v_mov_b32_dpp v89, v76 row_ror:8 row_mask:0xf bank_mask:0xf
	v_mov_b32_dpp v90, v77 row_ror:8 row_mask:0xf bank_mask:0xf
	v_lshlrev_b32_e32 v74, 16, v4
	v_and_b32_e32 v75, 0xffff0000, v4
	v_lshlrev_b32_e32 v76, 16, v84
	v_and_b32_e32 v77, 0xffff0000, v84
	v_lshlrev_b32_e32 v78, 16, v85
	v_and_b32_e32 v79, 0xffff0000, v85
	v_lshlrev_b32_e32 v80, 16, v86
	v_and_b32_e32 v81, 0xffff0000, v86
	v_pk_mul_f32 v[70:71], v[70:71], v[76:77]
	v_pk_mul_f32 v[68:69], v[68:69], v[74:75]
	v_pk_mul_f32 v[66:67], v[66:67], v[80:81]
	v_pk_mul_f32 v[64:65], v[64:65], v[78:79]
	v_cvt_pk_bf16_f32 v4, v68, v69
	v_cvt_pk_bf16_f32 v68, v70, v71
	v_lshlrev_b32_e32 v74, 16, v89
	v_cvt_pk_bf16_f32 v69, v64, v65
	v_cvt_pk_bf16_f32 v70, v66, v67
	v_lshlrev_b32_e32 v64, 16, v87
	v_and_b32_e32 v65, 0xffff0000, v87
	v_lshlrev_b32_e32 v66, 16, v88
	v_and_b32_e32 v67, 0xffff0000, v88
	v_and_b32_e32 v75, 0xffff0000, v89
	v_lshlrev_b32_e32 v76, 16, v90
	v_and_b32_e32 v77, 0xffff0000, v90
	v_pk_mul_f32 v[62:63], v[62:63], v[66:67]
	v_pk_mul_f32 v[60:61], v[60:61], v[64:65]
	v_pk_mul_f32 v[58:59], v[58:59], v[76:77]
	v_pk_mul_f32 v[56:57], v[56:57], v[74:75]
	v_cvt_pk_bf16_f32 v60, v60, v61
	v_cvt_pk_bf16_f32 v61, v62, v63
	v_lshl_add_u64 v[64:65], s[40:41], 0, v[82:83]
	v_cvt_pk_bf16_f32 v62, v56, v57
	v_cvt_pk_bf16_f32 v63, v58, v59
	v_mov_b32_e32 v56, v5
	v_mov_b32_e32 v57, v5
	v_mov_b32_e32 v58, v5
	v_mov_b32_e32 v59, v5
	v_mov_b32_dpp v56, v60 row_ror:8 row_mask:0xf bank_mask:0xf
	v_mov_b32_dpp v57, v61 row_ror:8 row_mask:0xf bank_mask:0xf
	v_mov_b32_dpp v58, v62 row_ror:8 row_mask:0xf bank_mask:0xf
	v_mov_b32_dpp v59, v63 row_ror:8 row_mask:0xf bank_mask:0xf
	v_lshl_add_u64 v[66:67], v[64:65], 0, s[58:59]
	v_mov_b32_e32 v60, v4
	v_mov_b32_e32 v61, v68
	v_mov_b32_e32 v62, v69
	v_mov_b32_e32 v63, v70
	s_and_saveexec_b64 s[26:27], s[8:9]
	s_cbranch_execz .LBB0_794
	v_lshl_add_u64 v[74:75], v[64:65], 0, s[60:61]
	v_mov_b64_e32 v[66:67], v[64:65]
	v_mov_b32_e32 v60, v56
	v_mov_b32_e32 v61, v57
	v_mov_b32_e32 v62, v58
	v_mov_b32_e32 v63, v59
	v_mov_b32_e32 v56, v4
	v_mov_b32_e32 v57, v68
	v_mov_b32_e32 v58, v69
	v_mov_b32_e32 v59, v70
	v_mov_b64_e32 v[64:65], v[74:75]
.LBB0_794:
	s_or_b64 exec, exec, s[26:27]
	global_store_dwordx4 v[66:67], v[56:59], off sc1
	global_store_dwordx4 v[64:65], v[60:63], off sc1
	v_lshl_add_u64 v[64:65], v[72:73], 1, v[164:165]
	v_lshl_add_u64 v[56:57], s[46:47], 0, v[64:65]
	v_lshl_add_u64 v[58:59], v[56:57], 0, v[148:149]
	v_lshl_add_u64 v[60:61], v[56:57], 0, v[150:151]
	v_mov_b32_e32 v69, v5
	v_mov_b32_e32 v70, v5
	v_mov_b32_e32 v71, v5
	v_mov_b32_e32 v72, v5
	s_waitcnt vmcnt(14)
	v_cndmask_b32_e64 v4, v240, v236, s[8:9]
	v_cndmask_b32_e64 v66, v241, v237, s[8:9]
	v_cndmask_b32_e64 v67, v242, v238, s[8:9]
	v_cndmask_b32_e64 v68, v243, v239, s[8:9]
	v_cndmask_b32_e64 v56, v236, v240, s[8:9]
	v_cndmask_b32_e64 v57, v237, v241, s[8:9]
	v_cndmask_b32_e64 v58, v238, v242, s[8:9]
	v_cndmask_b32_e64 v59, v239, v243, s[8:9]
	v_mov_b32_dpp v69, v56 row_ror:8 row_mask:0xf bank_mask:0xf
	v_mov_b32_dpp v70, v57 row_ror:8 row_mask:0xf bank_mask:0xf
	v_mov_b32_dpp v71, v58 row_ror:8 row_mask:0xf bank_mask:0xf
	v_mov_b32_dpp v72, v59 row_ror:8 row_mask:0xf bank_mask:0xf
	v_lshlrev_b32_e32 v56, 16, v4
	v_and_b32_e32 v57, 0xffff0000, v4
	v_lshlrev_b32_e32 v58, 16, v66
	v_and_b32_e32 v59, 0xffff0000, v66
	v_lshlrev_b32_e32 v60, 16, v67
	v_and_b32_e32 v61, 0xffff0000, v67
	v_lshlrev_b32_e32 v62, 16, v68
	v_and_b32_e32 v63, 0xffff0000, v68
	v_pk_mul_f32 v[54:55], v[54:55], v[58:59]
	v_pk_mul_f32 v[52:53], v[52:53], v[56:57]
	v_pk_mul_f32 v[50:51], v[50:51], v[62:63]
	v_pk_mul_f32 v[48:49], v[48:49], v[60:61]
	v_cvt_pk_bf16_f32 v4, v52, v53
	v_cvt_pk_bf16_f32 v52, v54, v55
	v_lshlrev_b32_e32 v56, 16, v71
	v_cvt_pk_bf16_f32 v53, v48, v49
	v_cvt_pk_bf16_f32 v54, v50, v51
	v_lshlrev_b32_e32 v48, 16, v69
	v_and_b32_e32 v49, 0xffff0000, v69
	v_lshlrev_b32_e32 v50, 16, v70
	v_and_b32_e32 v51, 0xffff0000, v70
	v_and_b32_e32 v57, 0xffff0000, v71
	v_lshlrev_b32_e32 v58, 16, v72
	v_and_b32_e32 v59, 0xffff0000, v72
	v_pk_mul_f32 v[46:47], v[46:47], v[50:51]
	v_pk_mul_f32 v[44:45], v[44:45], v[48:49]
	v_pk_mul_f32 v[42:43], v[42:43], v[58:59]
	v_pk_mul_f32 v[40:41], v[40:41], v[56:57]
	v_cvt_pk_bf16_f32 v44, v44, v45
	v_cvt_pk_bf16_f32 v45, v46, v47
	v_lshl_add_u64 v[48:49], s[40:41], 0, v[64:65]
	v_cvt_pk_bf16_f32 v46, v40, v41
	v_cvt_pk_bf16_f32 v47, v42, v43
	v_mov_b32_e32 v40, v5
	v_mov_b32_e32 v41, v5
	v_mov_b32_e32 v42, v5
	v_mov_b32_e32 v43, v5
	v_mov_b32_dpp v40, v44 row_ror:8 row_mask:0xf bank_mask:0xf
	v_mov_b32_dpp v41, v45 row_ror:8 row_mask:0xf bank_mask:0xf
	v_mov_b32_dpp v42, v46 row_ror:8 row_mask:0xf bank_mask:0xf
	v_mov_b32_dpp v43, v47 row_ror:8 row_mask:0xf bank_mask:0xf
	v_lshl_add_u64 v[50:51], v[48:49], 0, s[58:59]
	v_mov_b32_e32 v44, v4
	v_mov_b32_e32 v45, v52
	v_mov_b32_e32 v46, v53
	v_mov_b32_e32 v47, v54
	s_and_saveexec_b64 s[26:27], s[8:9]
	s_cbranch_execz .LBB0_796
	v_lshl_add_u64 v[56:57], v[48:49], 0, s[60:61]
	v_mov_b64_e32 v[50:51], v[48:49]
	v_mov_b32_e32 v44, v40
	v_mov_b32_e32 v45, v41
	v_mov_b32_e32 v46, v42
	v_mov_b32_e32 v47, v43
	v_mov_b32_e32 v40, v4
	v_mov_b32_e32 v41, v52
	v_mov_b32_e32 v42, v53
	v_mov_b32_e32 v43, v54
	v_mov_b64_e32 v[48:49], v[56:57]
.LBB0_796:
	s_or_b64 exec, exec, s[26:27]
	global_store_dwordx4 v[50:51], v[40:43], off sc1
	global_store_dwordx4 v[48:49], v[44:47], off sc1
	v_mov_b32_e32 v53, v5
	v_lshlrev_b64 v[40:41], 10, v[136:137]
	v_lshl_add_u64 v[6:7], v[40:41], 0, v[6:7]
	v_lshl_add_u64 v[48:49], v[6:7], 1, v[166:167]
	v_lshl_add_u64 v[40:41], s[46:47], 0, v[48:49]
	v_lshl_add_u64 v[42:43], v[40:41], 0, v[148:149]
	v_lshl_add_u64 v[44:45], v[40:41], 0, v[150:151]
	v_mov_b32_e32 v54, v5
	v_mov_b32_e32 v55, v5
	v_mov_b32_e32 v56, v5
	s_waitcnt vmcnt(14)
	v_cndmask_b32_e64 v4, v200, v196, s[8:9]
	v_cndmask_b32_e64 v50, v201, v197, s[8:9]
	v_cndmask_b32_e64 v51, v202, v198, s[8:9]
	v_cndmask_b32_e64 v52, v203, v199, s[8:9]
	v_cndmask_b32_e64 v40, v196, v200, s[8:9]
	v_cndmask_b32_e64 v41, v197, v201, s[8:9]
	v_cndmask_b32_e64 v42, v198, v202, s[8:9]
	v_cndmask_b32_e64 v43, v199, v203, s[8:9]
	v_mov_b32_dpp v53, v40 row_ror:8 row_mask:0xf bank_mask:0xf
	v_mov_b32_dpp v54, v41 row_ror:8 row_mask:0xf bank_mask:0xf
	v_mov_b32_dpp v55, v42 row_ror:8 row_mask:0xf bank_mask:0xf
	v_mov_b32_dpp v56, v43 row_ror:8 row_mask:0xf bank_mask:0xf
	v_lshlrev_b32_e32 v40, 16, v4
	v_and_b32_e32 v41, 0xffff0000, v4
	v_lshlrev_b32_e32 v42, 16, v50
	v_and_b32_e32 v43, 0xffff0000, v50
	v_lshlrev_b32_e32 v44, 16, v51
	v_and_b32_e32 v45, 0xffff0000, v51
	v_lshlrev_b32_e32 v46, 16, v52
	v_and_b32_e32 v47, 0xffff0000, v52
	v_pk_mul_f32 v[38:39], v[38:39], v[42:43]
	v_pk_mul_f32 v[36:37], v[36:37], v[40:41]
	v_pk_mul_f32 v[34:35], v[34:35], v[46:47]
	v_pk_mul_f32 v[32:33], v[32:33], v[44:45]
	v_cvt_pk_bf16_f32 v4, v36, v37
	v_cvt_pk_bf16_f32 v36, v38, v39
	v_lshlrev_b32_e32 v40, 16, v55
	v_cvt_pk_bf16_f32 v37, v32, v33
	v_cvt_pk_bf16_f32 v38, v34, v35
	v_lshlrev_b32_e32 v32, 16, v53
	v_and_b32_e32 v33, 0xffff0000, v53
	v_lshlrev_b32_e32 v34, 16, v54
	v_and_b32_e32 v35, 0xffff0000, v54
	v_and_b32_e32 v41, 0xffff0000, v55
	v_lshlrev_b32_e32 v42, 16, v56
	v_and_b32_e32 v43, 0xffff0000, v56
	v_pk_mul_f32 v[30:31], v[30:31], v[34:35]
	v_pk_mul_f32 v[28:29], v[28:29], v[32:33]
	v_pk_mul_f32 v[26:27], v[26:27], v[42:43]
	v_pk_mul_f32 v[24:25], v[24:25], v[40:41]
	v_cvt_pk_bf16_f32 v28, v28, v29
	v_cvt_pk_bf16_f32 v29, v30, v31
	v_lshl_add_u64 v[32:33], s[40:41], 0, v[48:49]
	v_cvt_pk_bf16_f32 v30, v24, v25
	v_cvt_pk_bf16_f32 v31, v26, v27
	v_mov_b32_e32 v24, v5
	v_mov_b32_e32 v25, v5
	v_mov_b32_e32 v26, v5
	v_mov_b32_e32 v27, v5
	v_mov_b32_dpp v24, v28 row_ror:8 row_mask:0xf bank_mask:0xf
	v_mov_b32_dpp v25, v29 row_ror:8 row_mask:0xf bank_mask:0xf
	v_mov_b32_dpp v26, v30 row_ror:8 row_mask:0xf bank_mask:0xf
	v_mov_b32_dpp v27, v31 row_ror:8 row_mask:0xf bank_mask:0xf
	v_lshl_add_u64 v[34:35], v[32:33], 0, s[58:59]
	v_mov_b32_e32 v28, v4
	v_mov_b32_e32 v29, v36
	v_mov_b32_e32 v30, v37
	v_mov_b32_e32 v31, v38
	s_and_saveexec_b64 s[26:27], s[8:9]
	s_cbranch_execz .LBB0_798
	v_lshl_add_u64 v[40:41], v[32:33], 0, s[60:61]
	v_mov_b64_e32 v[34:35], v[32:33]
	v_mov_b32_e32 v28, v24
	v_mov_b32_e32 v29, v25
	v_mov_b32_e32 v30, v26
	v_mov_b32_e32 v31, v27
	v_mov_b32_e32 v24, v4
	v_mov_b32_e32 v25, v36
	v_mov_b32_e32 v26, v37
	v_mov_b32_e32 v27, v38
	v_mov_b64_e32 v[32:33], v[40:41]
.LBB0_798:
	s_or_b64 exec, exec, s[26:27]
	v_lshl_add_u64 v[6:7], v[6:7], 1, v[168:169]
	global_store_dwordx4 v[34:35], v[24:27], off sc1
	global_store_dwordx4 v[32:33], v[28:31], off sc1
	v_mov_b32_e32 v35, v5
	v_lshl_add_u64 v[24:25], s[46:47], 0, v[6:7]
	v_lshl_add_u64 v[26:27], v[24:25], 0, v[148:149]
	v_lshl_add_u64 v[28:29], v[24:25], 0, v[150:151]
	v_mov_b32_e32 v36, v5
	v_mov_b32_e32 v37, v5
	v_mov_b32_e32 v38, v5
	s_waitcnt vmcnt(12)
	v_cndmask_b32_e64 v4, v208, v204, s[8:9]
	v_cndmask_b32_e64 v32, v209, v205, s[8:9]
	v_cndmask_b32_e64 v33, v210, v206, s[8:9]
	v_cndmask_b32_e64 v34, v211, v207, s[8:9]
	v_cndmask_b32_e64 v24, v204, v208, s[8:9]
	v_cndmask_b32_e64 v25, v205, v209, s[8:9]
	v_cndmask_b32_e64 v26, v206, v210, s[8:9]
	v_cndmask_b32_e64 v27, v207, v211, s[8:9]
	v_mov_b32_dpp v35, v24 row_ror:8 row_mask:0xf bank_mask:0xf
	v_mov_b32_dpp v36, v25 row_ror:8 row_mask:0xf bank_mask:0xf
	v_lshlrev_b32_e32 v24, 16, v4
	v_and_b32_e32 v25, 0xffff0000, v4
	v_lshlrev_b32_e32 v28, 16, v33
	v_and_b32_e32 v29, 0xffff0000, v33
	v_lshlrev_b32_e32 v30, 16, v34
	v_and_b32_e32 v31, 0xffff0000, v34
	v_mov_b32_dpp v37, v26 row_ror:8 row_mask:0xf bank_mask:0xf
	v_mov_b32_dpp v38, v27 row_ror:8 row_mask:0xf bank_mask:0xf
	v_lshlrev_b32_e32 v26, 16, v32
	v_and_b32_e32 v27, 0xffff0000, v32
	v_pk_mul_f32 v[20:21], v[20:21], v[24:25]
	v_pk_mul_f32 v[24:25], v[18:19], v[30:31]
	v_pk_mul_f32 v[16:17], v[16:17], v[28:29]
	v_pk_mul_f32 v[22:23], v[22:23], v[26:27]
	v_cvt_pk_bf16_f32 v4, v20, v21
	v_lshlrev_b32_e32 v26, 16, v38
	v_cvt_pk_bf16_f32 v18, v22, v23
	v_cvt_pk_bf16_f32 v19, v16, v17
	v_cvt_pk_bf16_f32 v20, v24, v25
	v_lshlrev_b32_e32 v16, 16, v35
	v_and_b32_e32 v17, 0xffff0000, v35
	v_lshlrev_b32_e32 v24, 16, v37
	v_and_b32_e32 v25, 0xffff0000, v37
	v_lshlrev_b32_e32 v22, 16, v36
	v_and_b32_e32 v23, 0xffff0000, v36
	v_and_b32_e32 v27, 0xffff0000, v38
	v_pk_mul_f32 v[12:13], v[12:13], v[16:17]
	v_pk_mul_f32 v[8:9], v[8:9], v[24:25]
	v_pk_mul_f32 v[14:15], v[14:15], v[22:23]
	v_pk_mul_f32 v[10:11], v[10:11], v[26:27]
	v_cvt_pk_bf16_f32 v12, v12, v13
	v_cvt_pk_bf16_f32 v13, v14, v15
	v_cvt_pk_bf16_f32 v9, v8, v9
	v_mov_b32_e32 v8, v5
	v_cvt_pk_bf16_f32 v10, v10, v11
	v_lshl_add_u64 v[14:15], s[40:41], 0, v[6:7]
	v_mov_b32_e32 v6, v5
	v_mov_b32_e32 v7, v5
	v_mov_b32_dpp v8, v9 row_ror:8 row_mask:0xf bank_mask:0xf
	v_mov_b32_e32 v9, v5
	v_mov_b32_dpp v6, v12 row_ror:8 row_mask:0xf bank_mask:0xf
	v_mov_b32_dpp v7, v13 row_ror:8 row_mask:0xf bank_mask:0xf
	v_mov_b32_dpp v9, v10 row_ror:8 row_mask:0xf bank_mask:0xf
	v_lshl_add_u64 v[16:17], v[14:15], 0, s[58:59]
	v_mov_b32_e32 v10, v4
	v_mov_b32_e32 v11, v18
	v_mov_b32_e32 v12, v19
	v_mov_b32_e32 v13, v20
	s_and_saveexec_b64 s[26:27], s[8:9]
	s_cbranch_execz .LBB0_800
	v_lshl_add_u64 v[22:23], v[14:15], 0, s[60:61]
	v_mov_b64_e32 v[16:17], v[14:15]
	v_mov_b32_e32 v10, v6
	v_mov_b32_e32 v11, v7
	v_mov_b32_e32 v12, v8
	v_mov_b32_e32 v13, v9
	v_mov_b32_e32 v6, v4
	v_mov_b32_e32 v7, v18
	v_mov_b32_e32 v8, v19
	v_mov_b32_e32 v9, v20
	v_mov_b64_e32 v[14:15], v[22:23]
.LBB0_800:
	s_or_b64 exec, exec, s[26:27]
	s_and_b64 vcc, exec, s[10:11]
	s_mov_b64 s[10:11], -1
	global_store_dwordx4 v[16:17], v[6:9], off sc1
	global_store_dwordx4 v[14:15], v[10:13], off sc1
	s_cbranch_vccnz .LBB0_767
	s_andn2_b64 vcc, exec, s[22:23]
	s_cbranch_vccnz .LBB0_766
	s_barrier
	s_branch .LBB0_766
